# speedup vs baseline: 1.0032x; 1.0032x over previous
; #define LAS __attribute__((address_space(3)))
; template <int S> __device__ __forceinline__ void fsm_chunk(f32x16& c0, f32x16& c1, float& ps, bf16x8& pa0, bf16x8& pa1, bf16x8& pa2, bf16x8& pa3) {
;   if constexpr (S < 8) { c1[2 * S] = __builtin_amdgcn_exp2f(c1[2 * S]); c1[2 * S + 1] = __builtin_amdgcn_exp2f(c1[2 * S + 1]); ps += c0[2 * S]; ps += c0[2 * S + 1]; if constexpr (S > 0) { ps += c1[2 * S - 2]; ps += c1[2 * S - 1]; } asm volatile("" : "+v"(c1), "+v"(ps)); }
;   else if constexpr (S == 8) { ps += c1[14]; ps += c1[15]; PK4(c0, 0, pa0); asm volatile("" : "+v"(pa0), "+v"(ps)); }
;   else if constexpr (S == 9) { PK4(c0, 8, pa1); asm volatile("" : "+v"(pa1)); }
;   else if constexpr (S == 10) { PK4(c1, 0, pa2); asm volatile("" : "+v"(pa2)); }
;   else { PK4(c1, 8, pa3); asm volatile("" : "+v"(pa3)); }
; }
; __device__ __forceinline__ void qk_fsm(f32x16& n0, f32x16& n1, f32x16& c0, f32x16& c1, float alC, float& l_reg, bf16x8& pa0, bf16x8& pa1, bf16x8& pa2, bf16x8& pa3,
;                                        const LAS char* kl, const int (&kx)[4], const bf16x8* qr, const LAS char* qrl) {
;   float ps = 0.f;
;     ...
;   QSLOT(0) QSLOT(1) QSLOT(2) QSLOT(3) QSLOT(4) QSLOT(5) QSLOT(6) QSLOT(7) QSLOT(8) QSLOT(9) QSLOT(10) QSLOT(11)
;     ...
;   { auto rr = __builtin_amdgcn_permlane32_swap(__float_as_uint(ps), __float_as_uint(ps), false, false); ps = __uint_as_float(rr[0]) + __uint_as_float(rr[1]); }
;   l_reg = l_reg * alC + ps;
; }
.LBB0_1011:
	s_add_u32 s4, s12, s31
	s_addc_u32 s5, s13, s9
	s_add_u32 s4, s4, 0x1dd0c000
	s_addc_u32 s5, s5, 0
	s_add_u32 s6, s12, s90
	s_addc_u32 s7, s13, s91
	s_add_u32 s6, s6, 0x25504000
	s_addc_u32 s7, s7, 0
	s_waitcnt lgkmcnt(0)
	ds_read_b128 v[244:247], v186 offset:57600
	ds_read_b128 v[248:251], v187 offset:12544
	ds_read_b128 v[238:241], v215
	v_exp_f32_e32 v64, v64
	v_exp_f32_e32 v65, v65
	v_mfma_f32_32x32x16_bf16 v[112:127], v[230:233], v[128:131], 0
	v_add_f32_e32 v96, 0, v80
	v_add_f32_e32 v162, v81, v96
	s_add_i32 m0, s98, 0x8000
	v_mfma_f32_32x32x16_bf16 v[96:111], v[234:237], v[128:131], 0
	global_load_lds_dwordx4 v177, s[4:5]
	s_waitcnt lgkmcnt(0)
	ds_read_b128 v[230:233], v188 offset:57344
	ds_read_b128 v[234:237], v189 offset:12288
	v_add_f32_e32 v162, v82, v162
	v_add_f32_e32 v162, v83, v162
	v_add_f32_e32 v162, v64, v162
	v_mfma_f32_32x32x16_bf16 v[112:127], v[244:247], v[238:241], v[112:127]
	v_exp_f32_e32 v66, v66
	v_exp_f32_e32 v67, v67
	v_add_f32_e32 v162, v65, v162
	s_add_i32 m0, s98, 0xa000
	v_mfma_f32_32x32x16_bf16 v[96:111], v[248:251], v[238:241], v[96:111]
	global_load_lds_dwordx4 v178, s[4:5]
	s_waitcnt lgkmcnt(0)
	ds_read_b128 v[244:247], v188 offset:57600
	ds_read_b128 v[248:251], v189 offset:12544
	ds_read_b128 v[238:241], v215 offset:1024
	v_add_f32_e32 v162, v84, v162
	v_add_f32_e32 v162, v85, v162
	v_add_f32_e32 v162, v66, v162
	v_mfma_f32_32x32x16_bf16 v[112:127], v[230:233], v[132:135], v[112:127]
	v_exp_f32_e32 v68, v68
	v_exp_f32_e32 v69, v69
	v_add_f32_e32 v162, v67, v162
	s_add_i32 m0, s98, 0xc000
	v_mfma_f32_32x32x16_bf16 v[96:111], v[234:237], v[132:135], v[96:111]
	global_load_lds_dwordx4 v179, s[4:5]
	s_waitcnt lgkmcnt(0)
	ds_read_b128 v[230:233], v190 offset:57344
	ds_read_b128 v[234:237], v191 offset:12288
	v_add_f32_e32 v162, v86, v162
	v_add_f32_e32 v162, v87, v162
	v_add_f32_e32 v162, v68, v162
	v_mfma_f32_32x32x16_bf16 v[112:127], v[244:247], v[238:241], v[112:127]
	v_exp_f32_e32 v70, v70
	v_exp_f32_e32 v71, v71
	v_add_f32_e32 v162, v69, v162
	s_add_i32 m0, s98, 0x4000
	v_mfma_f32_32x32x16_bf16 v[96:111], v[248:251], v[238:241], v[96:111]
	global_load_lds_dwordx4 v180, s[6:7]
	s_waitcnt lgkmcnt(0)
	ds_read_b128 v[244:247], v190 offset:57600
	ds_read_b128 v[248:251], v191 offset:12544
	ds_read_b128 v[238:241], v215 offset:2048
	v_add_f32_e32 v162, v88, v162
	v_add_f32_e32 v162, v89, v162
	v_add_f32_e32 v162, v70, v162
	v_mfma_f32_32x32x16_bf16 v[112:127], v[230:233], v[136:139], v[112:127]
	v_exp_f32_e32 v72, v72
	v_exp_f32_e32 v73, v73
	v_add_f32_e32 v162, v71, v162
	s_add_i32 m0, s98, 0x6000
	v_mfma_f32_32x32x16_bf16 v[96:111], v[234:237], v[136:139], v[96:111]
	global_load_lds_dwordx4 v181, s[6:7]
	s_waitcnt lgkmcnt(0)
	ds_read_b128 v[230:233], v192 offset:57344
	ds_read_b128 v[234:237], v193 offset:12288
	v_add_f32_e32 v162, v90, v162
	v_add_f32_e32 v162, v91, v162
	v_add_f32_e32 v162, v72, v162
	v_mfma_f32_32x32x16_bf16 v[112:127], v[244:247], v[238:241], v[112:127]
	v_exp_f32_e32 v74, v74
	v_exp_f32_e32 v75, v75
	v_add_f32_e32 v162, v73, v162
	v_mfma_f32_32x32x16_bf16 v[96:111], v[248:251], v[238:241], v[96:111]
	s_waitcnt lgkmcnt(0)
	ds_read_b128 v[244:247], v192 offset:57600
	ds_read_b128 v[248:251], v193 offset:12544
	ds_read_b128 v[238:241], v215 offset:3072
	v_add_f32_e32 v162, v92, v162
	v_add_f32_e32 v162, v93, v162
	v_add_f32_e32 v162, v74, v162
	v_mfma_f32_32x32x16_bf16 v[112:127], v[230:233], v[156:159], v[112:127]
	v_exp_f32_e32 v76, v76
	v_exp_f32_e32 v77, v77
	v_add_f32_e32 v162, v75, v162
	v_mfma_f32_32x32x16_bf16 v[96:111], v[234:237], v[156:159], v[96:111]
	s_waitcnt lgkmcnt(0)
	ds_read_b128 v[230:233], v186 offset:57472
	ds_read_b128 v[234:237], v187 offset:12416
	v_add_f32_e32 v162, v94, v162
	v_add_f32_e32 v162, v95, v162
	v_add_f32_e32 v162, v76, v162
	v_mfma_f32_32x32x16_bf16 v[112:127], v[244:247], v[238:241], v[112:127]
	v_exp_f32_e32 v78, v78
	v_exp_f32_e32 v79, v79
	v_add_f32_e32 v162, v77, v162
	v_mfma_f32_32x32x16_bf16 v[96:111], v[248:251], v[238:241], v[96:111]
	s_waitcnt lgkmcnt(0)
	ds_read_b128 v[244:247], v188 offset:57472
	ds_read_b128 v[248:251], v189 offset:12416
	v_add_f32_e32 v162, v162, v78
	v_cvt_pk_bf16_f32 v80, v80, v81
	v_cvt_pk_bf16_f32 v81, v82, v83
	v_cvt_pk_bf16_f32 v82, v84, v85
	v_mfma_f32_32x32x16_bf16 v[112:127], v[230:233], v[152:155], v[112:127]
	v_cvt_pk_bf16_f32 v83, v86, v87
	v_add_f32_e32 v227, v79, v162
	v_permlane32_swap_b32_e32 v80, v82
	v_permlane32_swap_b32_e32 v81, v83
	v_mfma_f32_32x32x16_bf16 v[96:111], v[234:237], v[152:155], v[96:111]
	s_waitcnt lgkmcnt(0)
	ds_read_b128 v[230:233], v190 offset:57472
	ds_read_b128 v[234:237], v191 offset:12416
	v_cvt_pk_bf16_f32 v84, v88, v89
	v_cvt_pk_bf16_f32 v85, v90, v91
	v_cvt_pk_bf16_f32 v86, v92, v93
	v_mfma_f32_32x32x16_bf16 v[112:127], v[244:247], v[148:151], v[112:127]
	v_cvt_pk_bf16_f32 v87, v94, v95
	v_permlane32_swap_b32_e32 v84, v86
	v_mfma_f32_32x32x16_bf16 v[96:111], v[248:251], v[148:151], v[96:111]
	v_permlane32_swap_b32_e32 v85, v87
	s_waitcnt lgkmcnt(0)
	ds_read_b128 v[244:247], v192 offset:57472
	ds_read_b128 v[248:251], v193 offset:12416
	v_cvt_pk_bf16_f32 v64, v64, v65
	v_cvt_pk_bf16_f32 v65, v66, v67
	v_cvt_pk_bf16_f32 v66, v68, v69
	v_mfma_f32_32x32x16_bf16 v[112:127], v[230:233], v[144:147], v[112:127]
	v_cvt_pk_bf16_f32 v67, v70, v71
	v_permlane32_swap_b32_e32 v64, v66
	v_mfma_f32_32x32x16_bf16 v[96:111], v[234:237], v[144:147], v[96:111]
	v_permlane32_swap_b32_e32 v65, v67
	s_waitcnt lgkmcnt(0)
; #define LAS __attribute__((address_space(3)))
; __device__ __forceinline__ float fma_s(float a, float b, float c) { float d; asm volatile("v_fma_f32 %0, %1, %2, %3" : "=v"(d) : "v"(a), "v"(b), "v"(c)); return d; }
; template <int S> __device__ __forceinline__ void psm_chunk(f32x16& p0, f32x16& p1, float& mx, float& m_reg, float& alpha, float& mnC) {
;   constexpr float C = SCALE * 1.4426950408889634f; const float Cv = C;
;   if constexpr (S == 0) { mx = p0[0];
; #pragma unroll
;     for (int r = 1; r < 16; ++r) mx = fmaxf(mx, p0[r]); }
;   else if constexpr (S == 1) {
; #pragma unroll
;     for (int r = 0; r < 16; ++r) mx = fmaxf(mx, p1[r]);
;     { auto rr = __builtin_amdgcn_permlane32_swap(__float_as_uint(mx), __float_as_uint(mx), false, false); mx = fmaxf(__uint_as_float(rr[0]), __uint_as_float(rr[1])); }
;     const float mn = (mx - m_reg > THR / SCALE) ? fmaxf(m_reg, mx) : m_reg; alpha = __builtin_amdgcn_exp2f((m_reg - mn) * C); m_reg = mn; mnC = -mn * C; }
;   else if constexpr (S == 2) {
; #pragma unroll
;     for (int r = 0; r < 8; ++r) p0[r] = fma_s(p0[r], Cv, mnC); }
;   else if constexpr (S == 3) {
; #pragma unroll
;     for (int r = 8; r < 16; ++r) p0[r] = fma_s(p0[r], Cv, mnC);
; #pragma unroll
;     for (int r = 0; r < 4; ++r) p0[r] = __builtin_amdgcn_exp2f(p0[r]); }
;   else if constexpr (S == 4) {
; #pragma unroll
;     for (int r = 0; r < 8; ++r) p1[r] = fma_s(p1[r], Cv, mnC);
; #pragma unroll
;     for (int r = 4; r < 8; ++r) p0[r] = __builtin_amdgcn_exp2f(p0[r]); }
;   else if constexpr (S == 5) {
; #pragma unroll
;     for (int r = 8; r < 16; ++r) p1[r] = fma_s(p1[r], Cv, mnC);
; #pragma unroll
;     for (int r = 8; r < 12; ++r) p0[r] = __builtin_amdgcn_exp2f(p0[r]); }
;   else if constexpr (S == 6) {
; #pragma unroll
;     for (int r = 12; r < 16; ++r) p0[r] = __builtin_amdgcn_exp2f(p0[r]); }
;   if constexpr (S == 0 || S == 1) asm volatile("" : "+v"(mx), "+v"(alpha), "+v"(mnC), "+v"(m_reg));
;   else if constexpr (S < 7) asm volatile("" : "+v"(p0), "+v"(p1));
; }
; __device__ __forceinline__ void pv_psm(f32x16* o, const LAS char* vl, bf16x8 pa0, bf16x8 pa1, bf16x8 pa2, bf16x8 pa3, f32x16& n0, f32x16& n1, float& m_reg, float& alN) {
;   float mx = 0.f, mnC = 0.f;
;     ...
;   VSLOT(0) VSLOT(1) VSLOT(2) VSLOT(3) VSLOT(4) VSLOT(5) VSLOT(6) VSLOT(7)
	ds_read_b64_tr_b16 v[234:235], v184
	ds_read_b64_tr_b16 v[236:237], v184 offset:2048
	ds_read_b64_tr_b16 v[238:239], v184 offset:4096
	ds_read_b64_tr_b16 v[240:241], v184 offset:6144
	v_cvt_pk_bf16_f32 v68, v72, v73
	v_cvt_pk_bf16_f32 v69, v74, v75
	v_cvt_pk_bf16_f32 v70, v76, v77
	v_mfma_f32_32x32x16_bf16 v[112:127], v[244:247], v[140:143], v[112:127]
	v_cvt_pk_bf16_f32 v71, v78, v79
	v_permlane32_swap_b32_e32 v68, v70
	v_mfma_f32_32x32x16_bf16 v[96:111], v[248:251], v[140:143], v[96:111]
	v_permlane32_swap_b32_e32 v69, v71
	v_mov_b32_e32 v229, v227
	s_nop 1
	v_permlane32_swap_b32_e32 v227, v229
	s_waitcnt lgkmcnt(0)
	ds_read_b64_tr_b16 v[72:73], v184 offset:8192
	ds_read_b64_tr_b16 v[74:75], v184 offset:10240
	ds_read_b64_tr_b16 v[76:77], v184 offset:12288
	ds_read_b64_tr_b16 v[78:79], v184 offset:14336
	v_max_f32_e32 v88, v113, v113
	v_max_f32_e32 v89, v112, v112
	v_mfma_f32_32x32x16_bf16 v[0:15], v[80:83], v[234:237], v[0:15]
	v_max_f32_e32 v88, v89, v88
	v_max3_f32 v88, v88, v114, v115
	v_max3_f32 v88, v88, v116, v117
	v_max3_f32 v252, v88, v118, v119
	v_max3_f32 v252, v252, v120, v121
	v_max3_f32 v252, v252, v122, v123
	v_max3_f32 v252, v252, v124, v125
	v_mfma_f32_32x32x16_bf16 v[0:15], v[84:87], v[238:241], v[0:15]
	v_max3_f32 v88, v252, v126, v127
	s_waitcnt lgkmcnt(0)
	ds_read_b64_tr_b16 v[234:235], v184 offset:512
	ds_read_b64_tr_b16 v[236:237], v184 offset:2560
	ds_read_b64_tr_b16 v[238:239], v184 offset:4608
	ds_read_b64_tr_b16 v[240:241], v184 offset:6656
	v_max3_f32 v88, v88, v96, v97
	v_max3_f32 v88, v88, v98, v99
	v_max3_f32 v88, v88, v100, v101
	v_max3_f32 v88, v88, v102, v103
	v_mfma_f32_32x32x16_bf16 v[0:15], v[64:67], v[72:75], v[0:15]
	v_max3_f32 v88, v88, v104, v105
	v_max3_f32 v88, v88, v106, v107
	v_max3_f32 v88, v88, v108, v109
	v_max3_f32 v88, v88, v110, v111
	v_mov_b32_e32 v89, v88
	s_nop 1
	v_permlane32_swap_b32_e32 v88, v89
	v_max_f32_e32 v89, v89, v89
	v_max_f32_e32 v88, v88, v88
	v_max_f32_e32 v88, v88, v89
	v_mfma_f32_32x32x16_bf16 v[0:15], v[68:71], v[76:79], v[0:15]
	v_sub_f32_e32 v89, v88, v228
	v_cmp_lt_f32_e32 vcc, s29, v89
	v_max_f32_e32 v89, v228, v228
	v_max_f32_e32 v89, v89, v88
	v_cndmask_b32_e32 v230, v228, v89, vcc
	v_sub_f32_e32 v89, v228, v230
	v_mul_f32_e32 v89, 0x3dd53b94, v89
	v_exp_f32_e32 v223, v89
	v_mul_f32_e32 v89, 0xbdd53b94, v230
	s_waitcnt lgkmcnt(0)
	ds_read_b64_tr_b16 v[72:73], v184 offset:8704
	ds_read_b64_tr_b16 v[74:75], v184 offset:10752
	ds_read_b64_tr_b16 v[76:77], v184 offset:12800
	ds_read_b64_tr_b16 v[78:79], v184 offset:14848
	v_fma_f32 v112, v112, v211, v89
	v_fma_f32 v113, v113, v211, v89
	v_mfma_f32_32x32x16_bf16 v[48:63], v[80:83], v[234:237], v[48:63]
	v_fma_f32 v114, v114, v211, v89
	v_fma_f32 v115, v115, v211, v89
	v_fma_f32 v116, v116, v211, v89
	v_fma_f32 v117, v117, v211, v89
	v_fma_f32 v118, v118, v211, v89
	v_fma_f32 v119, v119, v211, v89
	v_mfma_f32_32x32x16_bf16 v[48:63], v[84:87], v[238:241], v[48:63]
	s_waitcnt lgkmcnt(0)
	ds_read_b64_tr_b16 v[234:235], v184 offset:1024
	ds_read_b64_tr_b16 v[236:237], v184 offset:3072
	ds_read_b64_tr_b16 v[238:239], v184 offset:5120
	ds_read_b64_tr_b16 v[240:241], v184 offset:7168
	v_fma_f32 v120, v120, v211, v89
	v_fma_f32 v121, v121, v211, v89
	v_mfma_f32_32x32x16_bf16 v[48:63], v[64:67], v[72:75], v[48:63]
	v_fma_f32 v122, v122, v211, v89
	v_fma_f32 v123, v123, v211, v89
	v_fma_f32 v124, v124, v211, v89
	v_exp_f32_e32 v112, v112
	v_exp_f32_e32 v113, v113
	v_exp_f32_e32 v114, v114
	v_exp_f32_e32 v115, v115
	v_mfma_f32_32x32x16_bf16 v[48:63], v[68:71], v[76:79], v[48:63]
	v_fma_f32 v125, v125, v211, v89
	v_fma_f32 v126, v126, v211, v89
	v_fma_f32 v127, v127, v211, v89
	s_nop 0
	s_waitcnt lgkmcnt(0)
	ds_read_b64_tr_b16 v[72:73], v184 offset:9216
	ds_read_b64_tr_b16 v[74:75], v184 offset:11264
	ds_read_b64_tr_b16 v[76:77], v184 offset:13312
	ds_read_b64_tr_b16 v[78:79], v184 offset:15360
	v_fma_f32 v96, v96, v211, v89
	v_fma_f32 v97, v97, v211, v89
	v_mfma_f32_32x32x16_bf16 v[32:47], v[80:83], v[234:237], v[32:47]
	v_fma_f32 v98, v98, v211, v89
	v_fma_f32 v99, v99, v211, v89
	v_fma_f32 v100, v100, v211, v89
	v_exp_f32_e32 v116, v116
	v_exp_f32_e32 v117, v117
	v_exp_f32_e32 v118, v118
	v_exp_f32_e32 v119, v119
	v_mfma_f32_32x32x16_bf16 v[32:47], v[84:87], v[238:241], v[32:47]
	v_fma_f32 v101, v101, v211, v89
	v_fma_f32 v102, v102, v211, v89
	v_fma_f32 v103, v103, v211, v89
	s_nop 0
	s_waitcnt lgkmcnt(0)
	ds_read_b64_tr_b16 v[234:235], v184 offset:1536
	ds_read_b64_tr_b16 v[236:237], v184 offset:3584
	ds_read_b64_tr_b16 v[238:239], v184 offset:5632
	ds_read_b64_tr_b16 v[240:241], v184 offset:7680
	v_fma_f32 v104, v104, v211, v89
	v_fma_f32 v105, v105, v211, v89
	v_mfma_f32_32x32x16_bf16 v[32:47], v[64:67], v[72:75], v[32:47]
	v_fma_f32 v106, v106, v211, v89
	v_fma_f32 v107, v107, v211, v89
	v_fma_f32 v108, v108, v211, v89
	v_exp_f32_e32 v120, v120
	v_exp_f32_e32 v121, v121
	v_exp_f32_e32 v122, v122
	v_exp_f32_e32 v123, v123
	v_mfma_f32_32x32x16_bf16 v[32:47], v[68:71], v[76:79], v[32:47]
	v_fma_f32 v109, v109, v211, v89
	v_fma_f32 v110, v110, v211, v89
	v_fma_f32 v111, v111, v211, v89
	s_nop 0
	s_waitcnt lgkmcnt(0)
	ds_read_b64_tr_b16 v[72:73], v184 offset:9728
	ds_read_b64_tr_b16 v[74:75], v184 offset:11776
	ds_read_b64_tr_b16 v[76:77], v184 offset:13824
	ds_read_b64_tr_b16 v[78:79], v184 offset:15872
	v_mfma_f32_32x32x16_bf16 v[16:31], v[80:83], v[234:237], v[16:31]
	v_mfma_f32_32x32x16_bf16 v[16:31], v[84:87], v[238:241], v[16:31]
	s_waitcnt lgkmcnt(0)
	v_cmp_gt_f32_e32 vcc, 1.0, v223
	s_waitcnt vmcnt(0) lgkmcnt(0)
	s_barrier
; __device__ __forceinline__ void qk_fsm(f32x16& n0, f32x16& n1, f32x16& c0, f32x16& c1, float alC, float& l_reg, bf16x8& pa0, bf16x8& pa1, bf16x8& pa2, bf16x8& pa3,
;                                        const LAS char* kl, const int (&kx)[4], const bf16x8* qr, const LAS char* qrl) {
;   float ps = 0.f;
; template <int S> __device__ __forceinline__ void psm_chunk(f32x16& p0, f32x16& p1, float& mx, float& m_reg, float& alpha, float& mnC) {
;   constexpr float C = SCALE * 1.4426950408889634f; const float Cv = C;
;   if constexpr (S == 0) { mx = p0[0];
; #pragma unroll
;     for (int r = 1; r < 16; ++r) mx = fmaxf(mx, p0[r]); }
;   else if constexpr (S == 1) {
; #pragma unroll
;     for (int r = 0; r < 16; ++r) mx = fmaxf(mx, p1[r]);
;     { auto rr = __builtin_amdgcn_permlane32_swap(__float_as_uint(mx), __float_as_uint(mx), false, false); mx = fmaxf(__uint_as_float(rr[0]), __uint_as_float(rr[1])); }
;     const float mn = (mx - m_reg > THR / SCALE) ? fmaxf(m_reg, mx) : m_reg; alpha = __builtin_amdgcn_exp2f((m_reg - mn) * C); m_reg = mn; mnC = -mn * C; }
;   else if constexpr (S == 2) {
; #pragma unroll
;     for (int r = 0; r < 8; ++r) p0[r] = fma_s(p0[r], Cv, mnC); }
;   else if constexpr (S == 3) {
; #pragma unroll
;     for (int r = 8; r < 16; ++r) p0[r] = fma_s(p0[r], Cv, mnC);
; #pragma unroll
;     for (int r = 0; r < 4; ++r) p0[r] = __builtin_amdgcn_exp2f(p0[r]); }
;   else if constexpr (S == 4) {
; #pragma unroll
;     for (int r = 0; r < 8; ++r) p1[r] = fma_s(p1[r], Cv, mnC);
; #pragma unroll
;     for (int r = 4; r < 8; ++r) p0[r] = __builtin_amdgcn_exp2f(p0[r]); }
;   else if constexpr (S == 5) {
; #pragma unroll
;     for (int r = 8; r < 16; ++r) p1[r] = fma_s(p1[r], Cv, mnC);
; #pragma unroll
;     for (int r = 8; r < 12; ++r) p0[r] = __builtin_amdgcn_exp2f(p0[r]); }
;   else if constexpr (S == 6) {
; #pragma unroll
;     for (int r = 12; r < 16; ++r) p0[r] = __builtin_amdgcn_exp2f(p0[r]); }
;   if constexpr (S == 0 || S == 1) asm volatile("" : "+v"(mx), "+v"(alpha), "+v"(mnC), "+v"(m_reg));
;   else if constexpr (S < 7) asm volatile("" : "+v"(p0), "+v"(p1));
; }
; __device__ __forceinline__ void pv_psm(f32x16* o, const LAS char* vl, bf16x8 pa0, bf16x8 pa1, bf16x8 pa2, bf16x8 pa3, f32x16& n0, f32x16& n1, float& m_reg, float& alN) {
;   float mx = 0.f, mnC = 0.f;
;     ...
;   VSLOT(0) VSLOT(1) VSLOT(2) VSLOT(3) VSLOT(4) VSLOT(5) VSLOT(6) VSLOT(7)
	ds_read_b128 v[232:235], v186 offset:32768
	ds_read_b128 v[236:239], v186 offset:45056
	v_mfma_f32_32x32x16_bf16 v[16:31], v[64:67], v[72:75], v[16:31]
	v_mfma_f32_32x32x16_bf16 v[16:31], v[68:71], v[76:79], v[16:31]
	v_exp_f32_e32 v124, v124
	v_exp_f32_e32 v125, v125
	v_exp_f32_e32 v126, v126
	v_exp_f32_e32 v127, v127
	s_cbranch_vccz .LBB0_1015
	s_and_saveexec_b64 s[6:7], s[40:41]
	ds_write_b32 v185, v223 offset:128
	s_or_b64 exec, exec, s[6:7]
	s_waitcnt lgkmcnt(0)
	ds_read_b128 v[64:67], v196 offset:224
	ds_read_b128 v[68:71], v196 offset:192
	ds_read_b128 v[72:75], v196 offset:160
	ds_read_b128 v[76:79], v196 offset:128
	s_waitcnt lgkmcnt(0)
	v_pk_mul_f32 v[12:13], v[12:13], v[64:65]
	v_pk_mul_f32 v[8:9], v[8:9], v[68:69]
	v_pk_mul_f32 v[4:5], v[4:5], v[72:73]
	v_pk_mul_f32 v[14:15], v[14:15], v[66:67]
	v_pk_mul_f32 v[10:11], v[10:11], v[70:71]
	v_pk_mul_f32 v[6:7], v[6:7], v[74:75]
	v_pk_mul_f32 v[2:3], v[2:3], v[78:79]
	v_pk_mul_f32 v[0:1], v[0:1], v[76:77]
	v_pk_mul_f32 v[60:61], v[60:61], v[64:65]
	v_pk_mul_f32 v[56:57], v[56:57], v[68:69]
	v_pk_mul_f32 v[52:53], v[52:53], v[72:73]
	v_pk_mul_f32 v[62:63], v[62:63], v[66:67]
	v_pk_mul_f32 v[58:59], v[58:59], v[70:71]
	v_pk_mul_f32 v[54:55], v[54:55], v[74:75]
	v_pk_mul_f32 v[50:51], v[50:51], v[78:79]
	v_pk_mul_f32 v[48:49], v[48:49], v[76:77]
	v_pk_mul_f32 v[44:45], v[44:45], v[64:65]
	v_pk_mul_f32 v[40:41], v[40:41], v[68:69]
	v_pk_mul_f32 v[36:37], v[36:37], v[72:73]
	v_pk_mul_f32 v[46:47], v[46:47], v[66:67]
	v_pk_mul_f32 v[42:43], v[42:43], v[70:71]
	v_pk_mul_f32 v[38:39], v[38:39], v[74:75]
	v_pk_mul_f32 v[34:35], v[34:35], v[78:79]
	v_pk_mul_f32 v[32:33], v[32:33], v[76:77]
	v_pk_mul_f32 v[28:29], v[28:29], v[64:65]
	v_pk_mul_f32 v[24:25], v[24:25], v[68:69]
	v_pk_mul_f32 v[20:21], v[20:21], v[72:73]
	v_pk_mul_f32 v[30:31], v[30:31], v[66:67]
	v_pk_mul_f32 v[26:27], v[26:27], v[70:71]
	v_pk_mul_f32 v[22:23], v[22:23], v[74:75]
	v_pk_mul_f32 v[18:19], v[18:19], v[78:79]
	v_pk_mul_f32 v[16:17], v[16:17], v[76:77]
.LBB0_1015:
	s_add_u32 s4, s12, s31
	s_addc_u32 s5, s13, s9
	s_add_u32 s4, s4, 0x1dd12000
	s_addc_u32 s5, s5, 0
	s_add_u32 s6, s12, s90
	s_addc_u32 s7, s13, s91
	s_add_u32 s6, s6, 0x25508000
	s_addc_u32 s7, s7, 0
	s_waitcnt lgkmcnt(0)
	ds_read_b128 v[244:247], v186 offset:33024
	ds_read_b128 v[248:251], v186 offset:45312
	ds_read_b128 v[240:243], v215
	v_exp_f32_e32 v96, v96
	v_exp_f32_e32 v97, v97
	v_mfma_f32_32x32x16_bf16 v[80:95], v[232:235], v[128:131], 0
	v_add_f32_e32 v64, 0, v112
	v_add_f32_e32 v162, v113, v64
	s_add_i32 m0, s98, 0xe000
	v_mfma_f32_32x32x16_bf16 v[64:79], v[236:239], v[128:131], 0
	global_load_lds_dwordx4 v177, s[4:5]
	s_waitcnt lgkmcnt(0)
	ds_read_b128 v[232:235], v188 offset:32768
	ds_read_b128 v[236:239], v188 offset:45056
	v_add_f32_e32 v162, v114, v162
	v_add_f32_e32 v162, v115, v162
	v_add_f32_e32 v162, v96, v162
	v_mfma_f32_32x32x16_bf16 v[80:95], v[244:247], v[240:243], v[80:95]
	v_exp_f32_e32 v98, v98
	v_exp_f32_e32 v99, v99
	v_add_f32_e32 v162, v97, v162
	s_add_i32 m0, s98, 0x10000
	v_mfma_f32_32x32x16_bf16 v[64:79], v[248:251], v[240:243], v[64:79]
	global_load_lds_dwordx4 v178, s[4:5]
	s_waitcnt lgkmcnt(0)
	ds_read_b128 v[244:247], v188 offset:33024
	ds_read_b128 v[248:251], v188 offset:45312
	ds_read_b128 v[240:243], v215 offset:1024
	v_add_f32_e32 v162, v116, v162
	v_add_f32_e32 v162, v117, v162
	v_add_f32_e32 v162, v98, v162
	v_mfma_f32_32x32x16_bf16 v[80:95], v[232:235], v[132:135], v[80:95]
	v_exp_f32_e32 v100, v100
	v_exp_f32_e32 v101, v101
	v_add_f32_e32 v162, v99, v162
	s_add_i32 m0, s98, 0x12000
	v_mfma_f32_32x32x16_bf16 v[64:79], v[236:239], v[132:135], v[64:79]
	global_load_lds_dwordx4 v179, s[4:5]
	s_waitcnt lgkmcnt(0)
	ds_read_b128 v[232:235], v190 offset:32768
	ds_read_b128 v[236:239], v190 offset:45056
	v_add_f32_e32 v162, v118, v162
	v_add_f32_e32 v162, v119, v162
	v_add_f32_e32 v162, v100, v162
	v_mfma_f32_32x32x16_bf16 v[80:95], v[244:247], v[240:243], v[80:95]
	v_exp_f32_e32 v102, v102
	v_exp_f32_e32 v103, v103
	v_add_f32_e32 v162, v101, v162
	s_mov_b32 m0, s98
	v_mfma_f32_32x32x16_bf16 v[64:79], v[248:251], v[240:243], v[64:79]
	global_load_lds_dwordx4 v180, s[6:7]
	s_waitcnt lgkmcnt(0)
	ds_read_b128 v[244:247], v190 offset:33024
	ds_read_b128 v[248:251], v190 offset:45312
	ds_read_b128 v[240:243], v215 offset:2048
	v_add_f32_e32 v162, v120, v162
	v_add_f32_e32 v162, v121, v162
	v_add_f32_e32 v162, v102, v162
	v_mfma_f32_32x32x16_bf16 v[80:95], v[232:235], v[136:139], v[80:95]
	v_exp_f32_e32 v104, v104
	v_exp_f32_e32 v105, v105
	v_add_f32_e32 v162, v103, v162
	s_add_i32 m0, s98, 0x2000
	v_mfma_f32_32x32x16_bf16 v[64:79], v[236:239], v[136:139], v[64:79]
	global_load_lds_dwordx4 v181, s[6:7]
	s_waitcnt lgkmcnt(0)
	ds_read_b128 v[232:235], v192 offset:32768
	ds_read_b128 v[236:239], v192 offset:45056
	v_add_f32_e32 v162, v122, v162
	v_add_f32_e32 v162, v123, v162
	v_add_f32_e32 v162, v104, v162
	v_mfma_f32_32x32x16_bf16 v[80:95], v[244:247], v[240:243], v[80:95]
	v_exp_f32_e32 v106, v106
	v_exp_f32_e32 v107, v107
	v_add_f32_e32 v162, v105, v162
	v_mfma_f32_32x32x16_bf16 v[64:79], v[248:251], v[240:243], v[64:79]
	s_waitcnt lgkmcnt(0)
	ds_read_b128 v[244:247], v192 offset:33024
	ds_read_b128 v[248:251], v192 offset:45312
	ds_read_b128 v[240:243], v215 offset:3072
	v_add_f32_e32 v162, v124, v162
	v_add_f32_e32 v162, v125, v162
	v_add_f32_e32 v162, v106, v162
	v_mfma_f32_32x32x16_bf16 v[80:95], v[232:235], v[156:159], v[80:95]
	v_exp_f32_e32 v108, v108
	v_exp_f32_e32 v109, v109
	v_add_f32_e32 v162, v107, v162
	v_mfma_f32_32x32x16_bf16 v[64:79], v[236:239], v[156:159], v[64:79]
	s_waitcnt lgkmcnt(0)
; #define LAS __attribute__((address_space(3)))
; __device__ __forceinline__ void qk_fsm(f32x16& n0, f32x16& n1, f32x16& c0, f32x16& c1, float alC, float& l_reg, bf16x8& pa0, bf16x8& pa1, bf16x8& pa2, bf16x8& pa3,
;                                        const LAS char* kl, const int (&kx)[4], const bf16x8* qr, const LAS char* qrl) {
;   float ps = 0.f;
;     ...
;   QSLOT(0) QSLOT(1) QSLOT(2) QSLOT(3) QSLOT(4) QSLOT(5) QSLOT(6) QSLOT(7) QSLOT(8) QSLOT(9) QSLOT(10) QSLOT(11)
;     ...
;   { auto rr = __builtin_amdgcn_permlane32_swap(__float_as_uint(ps), __float_as_uint(ps), false, false); ps = __uint_as_float(rr[0]) + __uint_as_float(rr[1]); }
;   l_reg = l_reg * alC + ps;
; }
; template <int S> __device__ __forceinline__ void psm_chunk(f32x16& p0, f32x16& p1, float& mx, float& m_reg, float& alpha, float& mnC) {
;   constexpr float C = SCALE * 1.4426950408889634f; const float Cv = C;
;   if constexpr (S == 0) { mx = p0[0];
; #pragma unroll
;     for (int r = 1; r < 16; ++r) mx = fmaxf(mx, p0[r]); }
;   else if constexpr (S == 1) {
; #pragma unroll
;     for (int r = 0; r < 16; ++r) mx = fmaxf(mx, p1[r]);
;     { auto rr = __builtin_amdgcn_permlane32_swap(__float_as_uint(mx), __float_as_uint(mx), false, false); mx = fmaxf(__uint_as_float(rr[0]), __uint_as_float(rr[1])); }
;     const float mn = (mx - m_reg > THR / SCALE) ? fmaxf(m_reg, mx) : m_reg; alpha = __builtin_amdgcn_exp2f((m_reg - mn) * C); m_reg = mn; mnC = -mn * C; }
;   else if constexpr (S == 2) {
; #pragma unroll
;     for (int r = 0; r < 8; ++r) p0[r] = fma_s(p0[r], Cv, mnC); }
;   else if constexpr (S == 3) {
; #pragma unroll
;     for (int r = 8; r < 16; ++r) p0[r] = fma_s(p0[r], Cv, mnC);
; #pragma unroll
;     for (int r = 0; r < 4; ++r) p0[r] = __builtin_amdgcn_exp2f(p0[r]); }
;   else if constexpr (S == 4) {
; #pragma unroll
;     for (int r = 0; r < 8; ++r) p1[r] = fma_s(p1[r], Cv, mnC);
; #pragma unroll
;     for (int r = 4; r < 8; ++r) p0[r] = __builtin_amdgcn_exp2f(p0[r]); }
;   else if constexpr (S == 5) {
; #pragma unroll
;     for (int r = 8; r < 16; ++r) p1[r] = fma_s(p1[r], Cv, mnC);
; #pragma unroll
;     for (int r = 8; r < 12; ++r) p0[r] = __builtin_amdgcn_exp2f(p0[r]); }
;   else if constexpr (S == 6) {
; #pragma unroll
;     for (int r = 12; r < 16; ++r) p0[r] = __builtin_amdgcn_exp2f(p0[r]); }
;   if constexpr (S == 0 || S == 1) asm volatile("" : "+v"(mx), "+v"(alpha), "+v"(mnC), "+v"(m_reg));
	ds_read_b128 v[232:235], v186 offset:32896
	ds_read_b128 v[236:239], v186 offset:45184
	v_add_f32_e32 v162, v126, v162
	v_add_f32_e32 v162, v127, v162
	v_add_f32_e32 v162, v108, v162
	v_mfma_f32_32x32x16_bf16 v[80:95], v[244:247], v[240:243], v[80:95]
	v_exp_f32_e32 v110, v110
	v_exp_f32_e32 v111, v111
	v_add_f32_e32 v162, v109, v162
	v_mfma_f32_32x32x16_bf16 v[64:79], v[248:251], v[240:243], v[64:79]
	s_waitcnt lgkmcnt(0)
	ds_read_b128 v[244:247], v188 offset:32896
	ds_read_b128 v[248:251], v188 offset:45184
	v_add_f32_e32 v162, v162, v110
	v_cvt_pk_bf16_f32 v112, v112, v113
	v_cvt_pk_bf16_f32 v113, v114, v115
	v_cvt_pk_bf16_f32 v114, v116, v117
	v_mfma_f32_32x32x16_bf16 v[80:95], v[232:235], v[152:155], v[80:95]
	v_cvt_pk_bf16_f32 v115, v118, v119
	v_add_f32_e32 v231, v111, v162
	v_permlane32_swap_b32_e32 v112, v114
	v_permlane32_swap_b32_e32 v113, v115
	v_mfma_f32_32x32x16_bf16 v[64:79], v[236:239], v[152:155], v[64:79]
	s_waitcnt lgkmcnt(0)
	ds_read_b128 v[232:235], v190 offset:32896
	ds_read_b128 v[236:239], v190 offset:45184
	v_cvt_pk_bf16_f32 v116, v120, v121
	v_cvt_pk_bf16_f32 v117, v122, v123
	v_cvt_pk_bf16_f32 v118, v124, v125
	v_mfma_f32_32x32x16_bf16 v[80:95], v[244:247], v[148:151], v[80:95]
	v_cvt_pk_bf16_f32 v119, v126, v127
	v_permlane32_swap_b32_e32 v116, v118
	v_mfma_f32_32x32x16_bf16 v[64:79], v[248:251], v[148:151], v[64:79]
	v_permlane32_swap_b32_e32 v117, v119
	s_waitcnt lgkmcnt(0)
	ds_read_b128 v[244:247], v192 offset:32896
	ds_read_b128 v[248:251], v192 offset:45184
	v_cvt_pk_bf16_f32 v96, v96, v97
	v_cvt_pk_bf16_f32 v97, v98, v99
	v_cvt_pk_bf16_f32 v98, v100, v101
	v_mfma_f32_32x32x16_bf16 v[80:95], v[232:235], v[144:147], v[80:95]
	v_cvt_pk_bf16_f32 v99, v102, v103
	v_permlane32_swap_b32_e32 v96, v98
	v_mfma_f32_32x32x16_bf16 v[64:79], v[236:239], v[144:147], v[64:79]
	v_permlane32_swap_b32_e32 v97, v99
	s_waitcnt lgkmcnt(0)
	ds_read_b64_tr_b16 v[232:233], v184 offset:16384
	ds_read_b64_tr_b16 v[234:235], v184 offset:18432
	ds_read_b64_tr_b16 v[236:237], v184 offset:20480
	ds_read_b64_tr_b16 v[238:239], v184 offset:22528
	v_cvt_pk_bf16_f32 v100, v104, v105
	v_cvt_pk_bf16_f32 v101, v106, v107
	v_cvt_pk_bf16_f32 v102, v108, v109
	v_mfma_f32_32x32x16_bf16 v[80:95], v[244:247], v[140:143], v[80:95]
	v_cvt_pk_bf16_f32 v103, v110, v111
	v_permlane32_swap_b32_e32 v100, v102
	v_mfma_f32_32x32x16_bf16 v[64:79], v[248:251], v[140:143], v[64:79]
	v_permlane32_swap_b32_e32 v101, v103
	v_mov_b32_e32 v104, v231
	s_nop 1
	v_permlane32_swap_b32_e32 v231, v104
	s_waitcnt lgkmcnt(0)
	ds_read_b64_tr_b16 v[106:107], v184 offset:24576
	ds_read_b64_tr_b16 v[108:109], v184 offset:26624
	ds_read_b64_tr_b16 v[120:121], v184 offset:28672
	ds_read_b64_tr_b16 v[122:123], v184 offset:30720
	v_max_f32_e32 v105, v81, v81
	v_max_f32_e32 v110, v80, v80
	v_mfma_f32_32x32x16_bf16 v[0:15], v[112:115], v[232:235], v[0:15]
	v_max_f32_e32 v105, v110, v105
	v_max3_f32 v105, v105, v82, v83
	v_max3_f32 v105, v105, v84, v85
	v_max3_f32 v105, v105, v86, v87
	v_max3_f32 v105, v105, v88, v89
	v_max3_f32 v105, v105, v90, v91
	v_max3_f32 v105, v105, v92, v93
	v_mfma_f32_32x32x16_bf16 v[0:15], v[116:119], v[236:239], v[0:15]
	v_max3_f32 v105, v105, v94, v95
	s_waitcnt lgkmcnt(0)
	ds_read_b64_tr_b16 v[232:233], v184 offset:16896
	ds_read_b64_tr_b16 v[234:235], v184 offset:18944
	ds_read_b64_tr_b16 v[236:237], v184 offset:20992
	ds_read_b64_tr_b16 v[238:239], v184 offset:23040
	v_max3_f32 v105, v105, v64, v65
	v_max3_f32 v105, v105, v66, v67
	v_max3_f32 v105, v105, v68, v69
	v_max3_f32 v105, v105, v70, v71
	v_mfma_f32_32x32x16_bf16 v[0:15], v[96:99], v[106:109], v[0:15]
	v_max3_f32 v105, v105, v72, v73
	v_max3_f32 v105, v105, v74, v75
	v_max3_f32 v105, v105, v76, v77
	v_max3_f32 v105, v105, v78, v79
	v_mov_b32_e32 v110, v105
	s_nop 1
	v_permlane32_swap_b32_e32 v105, v110
	v_max_f32_e32 v110, v110, v110
	v_max_f32_e32 v105, v105, v105
	v_max_f32_e32 v105, v105, v110
	v_mfma_f32_32x32x16_bf16 v[0:15], v[100:103], v[120:123], v[0:15]
	v_sub_f32_e32 v110, v105, v230
	v_cmp_lt_f32_e32 vcc, s29, v110
	v_max_f32_e32 v110, v230, v230
	v_max_f32_e32 v110, v110, v105
	v_cndmask_b32_e32 v228, v230, v110, vcc
	v_sub_f32_e32 v110, v230, v228
	v_mul_f32_e32 v110, 0x3dd53b94, v110
	v_exp_f32_e32 v162, v110
	v_mul_f32_e32 v110, 0xbdd53b94, v228
	s_waitcnt lgkmcnt(0)
	ds_read_b64_tr_b16 v[106:107], v184 offset:25088
	ds_read_b64_tr_b16 v[108:109], v184 offset:27136
	ds_read_b64_tr_b16 v[120:121], v184 offset:29184
	ds_read_b64_tr_b16 v[122:123], v184 offset:31232
	v_fma_f32 v80, v80, v211, v110
	v_fma_f32 v81, v81, v211, v110
	v_mfma_f32_32x32x16_bf16 v[48:63], v[112:115], v[232:235], v[48:63]
	v_fma_f32 v82, v82, v211, v110
	v_fma_f32 v83, v83, v211, v110
	v_fma_f32 v84, v84, v211, v110
	v_fma_f32 v85, v85, v211, v110
	v_fma_f32 v86, v86, v211, v110
	v_fma_f32 v87, v87, v211, v110
	v_mfma_f32_32x32x16_bf16 v[48:63], v[116:119], v[236:239], v[48:63]
	s_waitcnt lgkmcnt(0)
; #define LAS __attribute__((address_space(3)))
; template <int S> __device__ __forceinline__ void psm_chunk(f32x16& p0, f32x16& p1, float& mx, float& m_reg, float& alpha, float& mnC) {
;   constexpr float C = SCALE * 1.4426950408889634f; const float Cv = C;
;   if constexpr (S == 0) { mx = p0[0];
; #pragma unroll
;     for (int r = 1; r < 16; ++r) mx = fmaxf(mx, p0[r]); }
;   else if constexpr (S == 1) {
; #pragma unroll
;     for (int r = 0; r < 16; ++r) mx = fmaxf(mx, p1[r]);
;     { auto rr = __builtin_amdgcn_permlane32_swap(__float_as_uint(mx), __float_as_uint(mx), false, false); mx = fmaxf(__uint_as_float(rr[0]), __uint_as_float(rr[1])); }
;     const float mn = (mx - m_reg > THR / SCALE) ? fmaxf(m_reg, mx) : m_reg; alpha = __builtin_amdgcn_exp2f((m_reg - mn) * C); m_reg = mn; mnC = -mn * C; }
;   else if constexpr (S == 2) {
; #pragma unroll
;     for (int r = 0; r < 8; ++r) p0[r] = fma_s(p0[r], Cv, mnC); }
;   else if constexpr (S == 3) {
; #pragma unroll
;     for (int r = 8; r < 16; ++r) p0[r] = fma_s(p0[r], Cv, mnC);
; #pragma unroll
;     for (int r = 0; r < 4; ++r) p0[r] = __builtin_amdgcn_exp2f(p0[r]); }
;   else if constexpr (S == 4) {
; #pragma unroll
;     for (int r = 0; r < 8; ++r) p1[r] = fma_s(p1[r], Cv, mnC);
; #pragma unroll
;     for (int r = 4; r < 8; ++r) p0[r] = __builtin_amdgcn_exp2f(p0[r]); }
;   else if constexpr (S == 5) {
; #pragma unroll
;     for (int r = 8; r < 16; ++r) p1[r] = fma_s(p1[r], Cv, mnC);
; #pragma unroll
;     for (int r = 8; r < 12; ++r) p0[r] = __builtin_amdgcn_exp2f(p0[r]); }
;   else if constexpr (S == 6) {
; #pragma unroll
;     for (int r = 12; r < 16; ++r) p0[r] = __builtin_amdgcn_exp2f(p0[r]); }
;   if constexpr (S == 0 || S == 1) asm volatile("" : "+v"(mx), "+v"(alpha), "+v"(mnC), "+v"(m_reg));
;   else if constexpr (S < 7) asm volatile("" : "+v"(p0), "+v"(p1));
; }
; __device__ __forceinline__ void pv_psm(f32x16* o, const LAS char* vl, bf16x8 pa0, bf16x8 pa1, bf16x8 pa2, bf16x8 pa3, f32x16& n0, f32x16& n1, float& m_reg, float& alN) {
;   float mx = 0.f, mnC = 0.f;
;     ...
;   VSLOT(0) VSLOT(1) VSLOT(2) VSLOT(3) VSLOT(4) VSLOT(5) VSLOT(6) VSLOT(7)
; __device__ __forceinline__ void attn_unit(const bf16_t* __restrict__ Qb, const bf16_t* __restrict__ Kh, const bf16_t* __restrict__ Vh, bf16_t* __restrict__ Ob, float* __restrict__ ssq, char* lds, LAS unsigned char* ldsl, ...
;     ...
;   constexpr int NT = SEQ / KVBLK;
	ds_read_b64_tr_b16 v[232:233], v184 offset:17408
	ds_read_b64_tr_b16 v[234:235], v184 offset:19456
	ds_read_b64_tr_b16 v[236:237], v184 offset:21504
	ds_read_b64_tr_b16 v[238:239], v184 offset:23552
	v_fma_f32 v88, v88, v211, v110
	v_fma_f32 v89, v89, v211, v110
	v_mfma_f32_32x32x16_bf16 v[48:63], v[96:99], v[106:109], v[48:63]
	v_fma_f32 v90, v90, v211, v110
	v_fma_f32 v91, v91, v211, v110
	v_fma_f32 v92, v92, v211, v110
	v_exp_f32_e32 v80, v80
	v_exp_f32_e32 v81, v81
	v_exp_f32_e32 v82, v82
	v_exp_f32_e32 v83, v83
	v_mfma_f32_32x32x16_bf16 v[48:63], v[100:103], v[120:123], v[48:63]
	v_fma_f32 v93, v93, v211, v110
	v_fma_f32 v94, v94, v211, v110
	v_fma_f32 v95, v95, v211, v110
	s_nop 0
	s_waitcnt lgkmcnt(0)
	ds_read_b64_tr_b16 v[106:107], v184 offset:25600
	ds_read_b64_tr_b16 v[108:109], v184 offset:27648
	ds_read_b64_tr_b16 v[120:121], v184 offset:29696
	ds_read_b64_tr_b16 v[122:123], v184 offset:31744
	v_fma_f32 v64, v64, v211, v110
	v_fma_f32 v65, v65, v211, v110
	v_mfma_f32_32x32x16_bf16 v[32:47], v[112:115], v[232:235], v[32:47]
	v_fma_f32 v66, v66, v211, v110
	v_fma_f32 v67, v67, v211, v110
	v_fma_f32 v68, v68, v211, v110
	v_exp_f32_e32 v84, v84
	v_exp_f32_e32 v85, v85
	v_exp_f32_e32 v86, v86
	v_exp_f32_e32 v87, v87
	v_mfma_f32_32x32x16_bf16 v[32:47], v[116:119], v[236:239], v[32:47]
	v_fma_f32 v69, v69, v211, v110
	v_fma_f32 v70, v70, v211, v110
	v_fma_f32 v71, v71, v211, v110
	s_nop 0
	s_waitcnt lgkmcnt(0)
	ds_read_b64_tr_b16 v[232:233], v184 offset:17920
	ds_read_b64_tr_b16 v[234:235], v184 offset:19968
	ds_read_b64_tr_b16 v[236:237], v184 offset:22016
	ds_read_b64_tr_b16 v[238:239], v184 offset:24064
	v_fma_f32 v72, v72, v211, v110
	v_fma_f32 v73, v73, v211, v110
	v_mfma_f32_32x32x16_bf16 v[32:47], v[96:99], v[106:109], v[32:47]
	v_fma_f32 v74, v74, v211, v110
	v_fma_f32 v75, v75, v211, v110
	v_fma_f32 v76, v76, v211, v110
	v_exp_f32_e32 v88, v88
	v_exp_f32_e32 v89, v89
	v_exp_f32_e32 v90, v90
	v_exp_f32_e32 v91, v91
	v_mfma_f32_32x32x16_bf16 v[32:47], v[100:103], v[120:123], v[32:47]
	v_fma_f32 v77, v77, v211, v110
	v_fma_f32 v78, v78, v211, v110
	v_fma_f32 v79, v79, v211, v110
	s_nop 0
	s_waitcnt lgkmcnt(0)
	ds_read_b64_tr_b16 v[106:107], v184 offset:26112
	ds_read_b64_tr_b16 v[108:109], v184 offset:28160
	ds_read_b64_tr_b16 v[120:121], v184 offset:30208
	ds_read_b64_tr_b16 v[122:123], v184 offset:32256
	v_mfma_f32_32x32x16_bf16 v[16:31], v[112:115], v[232:235], v[16:31]
	v_mfma_f32_32x32x16_bf16 v[16:31], v[116:119], v[236:239], v[16:31]
	s_waitcnt lgkmcnt(0)
	v_add_f32_e32 v252, v227, v229
	v_fmac_f32_e32 v252, v224, v171
	v_add_f32_e32 v171, v231, v104
	v_fmac_f32_e32 v171, v252, v223
	v_cmp_gt_f32_e32 vcc, 1.0, v162
	s_waitcnt vmcnt(0) lgkmcnt(0)
	s_barrier
	ds_read_b128 v[230:233], v186 offset:57344
	ds_read_b128 v[234:237], v187 offset:12288
	v_mfma_f32_32x32x16_bf16 v[16:31], v[96:99], v[106:109], v[16:31]
	v_mfma_f32_32x32x16_bf16 v[16:31], v[100:103], v[120:123], v[16:31]
	v_exp_f32_e32 v92, v92
	v_exp_f32_e32 v93, v93
	v_exp_f32_e32 v94, v94
	v_exp_f32_e32 v95, v95
	s_add_i32 s24, s24, 2
	s_add_u32 s31, s31, 0xc000
	s_addc_u32 s9, s9, 0
	s_add_u32 s90, s90, 0x8000
	s_addc_u32 s91, s91, 0
	s_cbranch_vccz .LBB0_1019
	s_and_saveexec_b64 s[6:7], s[40:41]
	ds_write_b32 v185, v162 offset:128
	s_or_b64 exec, exec, s[6:7]
	s_waitcnt lgkmcnt(0)
	ds_read_b128 v[96:99], v196 offset:224
	ds_read_b128 v[100:103], v196 offset:192
	ds_read_b128 v[106:109], v196 offset:160
	ds_read_b128 v[110:113], v196 offset:128
	s_waitcnt lgkmcnt(0)
	v_pk_mul_f32 v[12:13], v[12:13], v[96:97]
	v_pk_mul_f32 v[8:9], v[8:9], v[100:101]
	v_pk_mul_f32 v[4:5], v[4:5], v[106:107]
	v_pk_mul_f32 v[14:15], v[14:15], v[98:99]
	v_pk_mul_f32 v[10:11], v[10:11], v[102:103]
	v_pk_mul_f32 v[6:7], v[6:7], v[108:109]
	v_pk_mul_f32 v[2:3], v[2:3], v[112:113]
	v_pk_mul_f32 v[0:1], v[0:1], v[110:111]
	v_pk_mul_f32 v[60:61], v[60:61], v[96:97]
	v_pk_mul_f32 v[56:57], v[56:57], v[100:101]
	v_pk_mul_f32 v[52:53], v[52:53], v[106:107]
	v_pk_mul_f32 v[62:63], v[62:63], v[98:99]
	v_pk_mul_f32 v[58:59], v[58:59], v[102:103]
	v_pk_mul_f32 v[54:55], v[54:55], v[108:109]
	v_pk_mul_f32 v[50:51], v[50:51], v[112:113]
	v_pk_mul_f32 v[48:49], v[48:49], v[110:111]
	v_pk_mul_f32 v[44:45], v[44:45], v[96:97]
	v_pk_mul_f32 v[40:41], v[40:41], v[100:101]
	v_pk_mul_f32 v[36:37], v[36:37], v[106:107]
	v_pk_mul_f32 v[46:47], v[46:47], v[98:99]
	v_pk_mul_f32 v[42:43], v[42:43], v[102:103]
	v_pk_mul_f32 v[38:39], v[38:39], v[108:109]
	v_pk_mul_f32 v[34:35], v[34:35], v[112:113]
	v_pk_mul_f32 v[32:33], v[32:33], v[110:111]
	v_pk_mul_f32 v[28:29], v[28:29], v[96:97]
	v_pk_mul_f32 v[24:25], v[24:25], v[100:101]
	v_pk_mul_f32 v[20:21], v[20:21], v[106:107]
	v_pk_mul_f32 v[30:31], v[30:31], v[98:99]
	v_pk_mul_f32 v[26:27], v[26:27], v[102:103]
	v_pk_mul_f32 v[22:23], v[22:23], v[108:109]
	v_pk_mul_f32 v[18:19], v[18:19], v[112:113]
	v_pk_mul_f32 v[16:17], v[16:17], v[110:111]
